# up-GEMM epilogue regenerated: packed squares, in-place bf16 packing, scalar-base stores (46 vs 57 vector instr per row group, same arithmetic)
# baseline (speedup 1.0000x reference)
.LBB0_1147:
	v_lshl_add_u32 v144, s22, 8, v149
	v_lshl_or_b32 v140, s4, 8, v151
	s_mov_b64 s[22:23], -1
	v_lshlrev_b32_e32 v140, 1, v140
	v_lshl_add_u32 v140, v144, 13, v140
	v_fmamk_f32 v146, v228, 0x3a800000, v235
	v_rsq_f32_e32 v146, v146
	s_nop 0
	v_pk_mul_f32 v[124:125], v[124:125], v[146:147] op_sel_hi:[1,0]
	v_pk_mul_f32 v[126:127], v[126:127], v[146:147] op_sel_hi:[1,0]
	v_pk_mul_f32 v[120:121], v[120:121], v[146:147] op_sel_hi:[1,0]
	v_pk_mul_f32 v[122:123], v[122:123], v[146:147] op_sel_hi:[1,0]
	v_pk_mul_f32 v[116:117], v[116:117], v[146:147] op_sel_hi:[1,0]
	v_pk_mul_f32 v[118:119], v[118:119], v[146:147] op_sel_hi:[1,0]
	v_pk_mul_f32 v[112:113], v[112:113], v[146:147] op_sel_hi:[1,0]
	v_pk_mul_f32 v[114:115], v[114:115], v[146:147] op_sel_hi:[1,0]
	v_max_f32_e32 v124, 0, v124
	v_max_f32_e32 v125, 0, v125
	v_max_f32_e32 v126, 0, v126
	v_max_f32_e32 v127, 0, v127
	v_max_f32_e32 v120, 0, v120
	v_max_f32_e32 v121, 0, v121
	v_max_f32_e32 v122, 0, v122
	v_max_f32_e32 v123, 0, v123
	v_max_f32_e32 v116, 0, v116
	v_max_f32_e32 v117, 0, v117
	v_max_f32_e32 v118, 0, v118
	v_max_f32_e32 v119, 0, v119
	v_max_f32_e32 v112, 0, v112
	v_max_f32_e32 v113, 0, v113
	v_max_f32_e32 v114, 0, v114
	v_max_f32_e32 v115, 0, v115
	v_pk_mul_f32 v[124:125], v[124:125], v[124:125]
	v_pk_mul_f32 v[126:127], v[126:127], v[126:127]
	v_pk_mul_f32 v[120:121], v[120:121], v[120:121]
	v_pk_mul_f32 v[122:123], v[122:123], v[122:123]
	v_pk_mul_f32 v[116:117], v[116:117], v[116:117]
	v_pk_mul_f32 v[118:119], v[118:119], v[118:119]
	v_pk_mul_f32 v[112:113], v[112:113], v[112:113]
	v_pk_mul_f32 v[114:115], v[114:115], v[114:115]
	v_cvt_pk_bf16_f32 v124, v124, v125
	v_cvt_pk_bf16_f32 v125, v126, v127
	v_cvt_pk_bf16_f32 v126, v120, v121
	v_cvt_pk_bf16_f32 v127, v122, v123
	global_store_dwordx4 v140, v[124:127], s[36:37]
	v_cvt_pk_bf16_f32 v116, v116, v117
	v_cvt_pk_bf16_f32 v117, v118, v119
	v_cvt_pk_bf16_f32 v118, v112, v113
	v_cvt_pk_bf16_f32 v119, v114, v115
	global_store_dwordx4 v140, v[116:119], s[36:37] offset:256
	v_fmamk_f32 v146, v229, 0x3a800000, v235
	v_rsq_f32_e32 v146, v146
	v_add_u32_e32 v141, 0x20000, v140
	v_pk_mul_f32 v[108:109], v[108:109], v[146:147] op_sel_hi:[1,0]
	v_pk_mul_f32 v[110:111], v[110:111], v[146:147] op_sel_hi:[1,0]
	v_pk_mul_f32 v[104:105], v[104:105], v[146:147] op_sel_hi:[1,0]
	v_pk_mul_f32 v[106:107], v[106:107], v[146:147] op_sel_hi:[1,0]
	v_pk_mul_f32 v[100:101], v[100:101], v[146:147] op_sel_hi:[1,0]
	v_pk_mul_f32 v[102:103], v[102:103], v[146:147] op_sel_hi:[1,0]
	v_pk_mul_f32 v[96:97], v[96:97], v[146:147] op_sel_hi:[1,0]
	v_pk_mul_f32 v[98:99], v[98:99], v[146:147] op_sel_hi:[1,0]
	v_max_f32_e32 v108, 0, v108
	v_max_f32_e32 v109, 0, v109
	v_max_f32_e32 v110, 0, v110
	v_max_f32_e32 v111, 0, v111
	v_max_f32_e32 v104, 0, v104
	v_max_f32_e32 v105, 0, v105
	v_max_f32_e32 v106, 0, v106
	v_max_f32_e32 v107, 0, v107
	v_max_f32_e32 v100, 0, v100
	v_max_f32_e32 v101, 0, v101
	v_max_f32_e32 v102, 0, v102
	v_max_f32_e32 v103, 0, v103
	v_max_f32_e32 v96, 0, v96
	v_max_f32_e32 v97, 0, v97
	v_max_f32_e32 v98, 0, v98
	v_max_f32_e32 v99, 0, v99
	v_pk_mul_f32 v[108:109], v[108:109], v[108:109]
	v_pk_mul_f32 v[110:111], v[110:111], v[110:111]
	v_pk_mul_f32 v[104:105], v[104:105], v[104:105]
	v_pk_mul_f32 v[106:107], v[106:107], v[106:107]
	v_pk_mul_f32 v[100:101], v[100:101], v[100:101]
	v_pk_mul_f32 v[102:103], v[102:103], v[102:103]
	v_pk_mul_f32 v[96:97], v[96:97], v[96:97]
	v_pk_mul_f32 v[98:99], v[98:99], v[98:99]
	v_cvt_pk_bf16_f32 v108, v108, v109
	v_cvt_pk_bf16_f32 v109, v110, v111
	v_cvt_pk_bf16_f32 v110, v104, v105
	v_cvt_pk_bf16_f32 v111, v106, v107
	global_store_dwordx4 v141, v[108:111], s[36:37]
	v_cvt_pk_bf16_f32 v100, v100, v101
	v_cvt_pk_bf16_f32 v101, v102, v103
	v_cvt_pk_bf16_f32 v102, v96, v97
	v_cvt_pk_bf16_f32 v103, v98, v99
	global_store_dwordx4 v141, v[100:103], s[36:37] offset:256
	v_fmamk_f32 v146, v230, 0x3a800000, v235
	v_rsq_f32_e32 v146, v146
	v_add_u32_e32 v141, 0x40000, v140
	v_pk_mul_f32 v[92:93], v[92:93], v[146:147] op_sel_hi:[1,0]
	v_pk_mul_f32 v[94:95], v[94:95], v[146:147] op_sel_hi:[1,0]
	v_pk_mul_f32 v[88:89], v[88:89], v[146:147] op_sel_hi:[1,0]
	v_pk_mul_f32 v[90:91], v[90:91], v[146:147] op_sel_hi:[1,0]
	v_pk_mul_f32 v[84:85], v[84:85], v[146:147] op_sel_hi:[1,0]
	v_pk_mul_f32 v[86:87], v[86:87], v[146:147] op_sel_hi:[1,0]
	v_pk_mul_f32 v[80:81], v[80:81], v[146:147] op_sel_hi:[1,0]
	v_pk_mul_f32 v[82:83], v[82:83], v[146:147] op_sel_hi:[1,0]
	v_max_f32_e32 v92, 0, v92
	v_max_f32_e32 v93, 0, v93
	v_max_f32_e32 v94, 0, v94
	v_max_f32_e32 v95, 0, v95
	v_max_f32_e32 v88, 0, v88
	v_max_f32_e32 v89, 0, v89
	v_max_f32_e32 v90, 0, v90
	v_max_f32_e32 v91, 0, v91
	v_max_f32_e32 v84, 0, v84
	v_max_f32_e32 v85, 0, v85
	v_max_f32_e32 v86, 0, v86
	v_max_f32_e32 v87, 0, v87
	v_max_f32_e32 v80, 0, v80
	v_max_f32_e32 v81, 0, v81
	v_max_f32_e32 v82, 0, v82
	v_max_f32_e32 v83, 0, v83
	v_pk_mul_f32 v[92:93], v[92:93], v[92:93]
	v_pk_mul_f32 v[94:95], v[94:95], v[94:95]
	v_pk_mul_f32 v[88:89], v[88:89], v[88:89]
	v_pk_mul_f32 v[90:91], v[90:91], v[90:91]
	v_pk_mul_f32 v[84:85], v[84:85], v[84:85]
	v_pk_mul_f32 v[86:87], v[86:87], v[86:87]
	v_pk_mul_f32 v[80:81], v[80:81], v[80:81]
	v_pk_mul_f32 v[82:83], v[82:83], v[82:83]
	v_cvt_pk_bf16_f32 v92, v92, v93
	v_cvt_pk_bf16_f32 v93, v94, v95
	v_cvt_pk_bf16_f32 v94, v88, v89
	v_cvt_pk_bf16_f32 v95, v90, v91
	global_store_dwordx4 v141, v[92:95], s[36:37]
	v_cvt_pk_bf16_f32 v84, v84, v85
	v_cvt_pk_bf16_f32 v85, v86, v87
	v_cvt_pk_bf16_f32 v86, v80, v81
	v_cvt_pk_bf16_f32 v87, v82, v83
	global_store_dwordx4 v141, v[84:87], s[36:37] offset:256
	v_fmamk_f32 v146, v231, 0x3a800000, v235
	v_rsq_f32_e32 v146, v146
	v_add_u32_e32 v141, 0x60000, v140
	v_pk_mul_f32 v[76:77], v[76:77], v[146:147] op_sel_hi:[1,0]
	v_pk_mul_f32 v[78:79], v[78:79], v[146:147] op_sel_hi:[1,0]
	v_pk_mul_f32 v[72:73], v[72:73], v[146:147] op_sel_hi:[1,0]
	v_pk_mul_f32 v[74:75], v[74:75], v[146:147] op_sel_hi:[1,0]
	v_pk_mul_f32 v[68:69], v[68:69], v[146:147] op_sel_hi:[1,0]
	v_pk_mul_f32 v[70:71], v[70:71], v[146:147] op_sel_hi:[1,0]
	v_pk_mul_f32 v[64:65], v[64:65], v[146:147] op_sel_hi:[1,0]
	v_pk_mul_f32 v[66:67], v[66:67], v[146:147] op_sel_hi:[1,0]
	v_max_f32_e32 v76, 0, v76
	v_max_f32_e32 v77, 0, v77
	v_max_f32_e32 v78, 0, v78
	v_max_f32_e32 v79, 0, v79
	v_max_f32_e32 v72, 0, v72
	v_max_f32_e32 v73, 0, v73
	v_max_f32_e32 v74, 0, v74
	v_max_f32_e32 v75, 0, v75
	v_max_f32_e32 v68, 0, v68
	v_max_f32_e32 v69, 0, v69
	v_max_f32_e32 v70, 0, v70
	v_max_f32_e32 v71, 0, v71
	v_max_f32_e32 v64, 0, v64
	v_max_f32_e32 v65, 0, v65
	v_max_f32_e32 v66, 0, v66
	v_max_f32_e32 v67, 0, v67
	v_pk_mul_f32 v[76:77], v[76:77], v[76:77]
	v_pk_mul_f32 v[78:79], v[78:79], v[78:79]
	v_pk_mul_f32 v[72:73], v[72:73], v[72:73]
	v_pk_mul_f32 v[74:75], v[74:75], v[74:75]
	v_pk_mul_f32 v[68:69], v[68:69], v[68:69]
	v_pk_mul_f32 v[70:71], v[70:71], v[70:71]
	v_pk_mul_f32 v[64:65], v[64:65], v[64:65]
	v_pk_mul_f32 v[66:67], v[66:67], v[66:67]
	v_cvt_pk_bf16_f32 v76, v76, v77
	v_cvt_pk_bf16_f32 v77, v78, v79
	v_cvt_pk_bf16_f32 v78, v72, v73
	v_cvt_pk_bf16_f32 v79, v74, v75
	global_store_dwordx4 v141, v[76:79], s[36:37]
	v_cvt_pk_bf16_f32 v68, v68, v69
	v_cvt_pk_bf16_f32 v69, v70, v71
	v_cvt_pk_bf16_f32 v70, v64, v65
	v_cvt_pk_bf16_f32 v71, v66, v67
	global_store_dwordx4 v141, v[68:71], s[36:37] offset:256
	v_fmamk_f32 v146, v232, 0x3a800000, v235
	v_rsq_f32_e32 v146, v146
	v_add_u32_e32 v141, 0x100000, v140
	v_pk_mul_f32 v[60:61], v[60:61], v[146:147] op_sel_hi:[1,0]
	v_pk_mul_f32 v[62:63], v[62:63], v[146:147] op_sel_hi:[1,0]
	v_pk_mul_f32 v[56:57], v[56:57], v[146:147] op_sel_hi:[1,0]
	v_pk_mul_f32 v[58:59], v[58:59], v[146:147] op_sel_hi:[1,0]
	v_pk_mul_f32 v[52:53], v[52:53], v[146:147] op_sel_hi:[1,0]
	v_pk_mul_f32 v[54:55], v[54:55], v[146:147] op_sel_hi:[1,0]
	v_pk_mul_f32 v[48:49], v[48:49], v[146:147] op_sel_hi:[1,0]
	v_pk_mul_f32 v[50:51], v[50:51], v[146:147] op_sel_hi:[1,0]
	v_max_f32_e32 v60, 0, v60
	v_max_f32_e32 v61, 0, v61
	v_max_f32_e32 v62, 0, v62
	v_max_f32_e32 v63, 0, v63
	v_max_f32_e32 v56, 0, v56
	v_max_f32_e32 v57, 0, v57
	v_max_f32_e32 v58, 0, v58
	v_max_f32_e32 v59, 0, v59
	v_max_f32_e32 v52, 0, v52
	v_max_f32_e32 v53, 0, v53
	v_max_f32_e32 v54, 0, v54
	v_max_f32_e32 v55, 0, v55
	v_max_f32_e32 v48, 0, v48
	v_max_f32_e32 v49, 0, v49
	v_max_f32_e32 v50, 0, v50
	v_max_f32_e32 v51, 0, v51
	v_pk_mul_f32 v[60:61], v[60:61], v[60:61]
	v_pk_mul_f32 v[62:63], v[62:63], v[62:63]
	v_pk_mul_f32 v[56:57], v[56:57], v[56:57]
	v_pk_mul_f32 v[58:59], v[58:59], v[58:59]
	v_pk_mul_f32 v[52:53], v[52:53], v[52:53]
	v_pk_mul_f32 v[54:55], v[54:55], v[54:55]
	v_pk_mul_f32 v[48:49], v[48:49], v[48:49]
	v_pk_mul_f32 v[50:51], v[50:51], v[50:51]
	v_cvt_pk_bf16_f32 v60, v60, v61
	v_cvt_pk_bf16_f32 v61, v62, v63
	v_cvt_pk_bf16_f32 v62, v56, v57
	v_cvt_pk_bf16_f32 v63, v58, v59
	global_store_dwordx4 v141, v[60:63], s[36:37]
	v_cvt_pk_bf16_f32 v52, v52, v53
	v_cvt_pk_bf16_f32 v53, v54, v55
	v_cvt_pk_bf16_f32 v54, v48, v49
	v_cvt_pk_bf16_f32 v55, v50, v51
	global_store_dwordx4 v141, v[52:55], s[36:37] offset:256
	v_fmamk_f32 v146, v233, 0x3a800000, v235
	v_rsq_f32_e32 v146, v146
	v_add_u32_e32 v141, 0x120000, v140
	v_pk_mul_f32 v[44:45], v[44:45], v[146:147] op_sel_hi:[1,0]
	v_pk_mul_f32 v[46:47], v[46:47], v[146:147] op_sel_hi:[1,0]
	v_pk_mul_f32 v[40:41], v[40:41], v[146:147] op_sel_hi:[1,0]
	v_pk_mul_f32 v[42:43], v[42:43], v[146:147] op_sel_hi:[1,0]
	v_pk_mul_f32 v[36:37], v[36:37], v[146:147] op_sel_hi:[1,0]
	v_pk_mul_f32 v[38:39], v[38:39], v[146:147] op_sel_hi:[1,0]
	v_pk_mul_f32 v[32:33], v[32:33], v[146:147] op_sel_hi:[1,0]
	v_pk_mul_f32 v[34:35], v[34:35], v[146:147] op_sel_hi:[1,0]
	v_max_f32_e32 v44, 0, v44
	v_max_f32_e32 v45, 0, v45
	v_max_f32_e32 v46, 0, v46
	v_max_f32_e32 v47, 0, v47
	v_max_f32_e32 v40, 0, v40
	v_max_f32_e32 v41, 0, v41
	v_max_f32_e32 v42, 0, v42
	v_max_f32_e32 v43, 0, v43
	v_max_f32_e32 v36, 0, v36
	v_max_f32_e32 v37, 0, v37
	v_max_f32_e32 v38, 0, v38
	v_max_f32_e32 v39, 0, v39
	v_max_f32_e32 v32, 0, v32
	v_max_f32_e32 v33, 0, v33
	v_max_f32_e32 v34, 0, v34
	v_max_f32_e32 v35, 0, v35
	v_pk_mul_f32 v[44:45], v[44:45], v[44:45]
	v_pk_mul_f32 v[46:47], v[46:47], v[46:47]
	v_pk_mul_f32 v[40:41], v[40:41], v[40:41]
	v_pk_mul_f32 v[42:43], v[42:43], v[42:43]
	v_pk_mul_f32 v[36:37], v[36:37], v[36:37]
	v_pk_mul_f32 v[38:39], v[38:39], v[38:39]
	v_pk_mul_f32 v[32:33], v[32:33], v[32:33]
	v_pk_mul_f32 v[34:35], v[34:35], v[34:35]
	v_cvt_pk_bf16_f32 v44, v44, v45
	v_cvt_pk_bf16_f32 v45, v46, v47
	v_cvt_pk_bf16_f32 v46, v40, v41
	v_cvt_pk_bf16_f32 v47, v42, v43
	global_store_dwordx4 v141, v[44:47], s[36:37]
	v_cvt_pk_bf16_f32 v36, v36, v37
	v_cvt_pk_bf16_f32 v37, v38, v39
	v_cvt_pk_bf16_f32 v38, v32, v33
	v_cvt_pk_bf16_f32 v39, v34, v35
	global_store_dwordx4 v141, v[36:39], s[36:37] offset:256
	v_fmamk_f32 v146, v190, 0x3a800000, v235
	v_rsq_f32_e32 v146, v146
	v_add_u32_e32 v141, 0x140000, v140
	v_pk_mul_f32 v[28:29], v[28:29], v[146:147] op_sel_hi:[1,0]
	v_pk_mul_f32 v[30:31], v[30:31], v[146:147] op_sel_hi:[1,0]
	v_pk_mul_f32 v[24:25], v[24:25], v[146:147] op_sel_hi:[1,0]
	v_pk_mul_f32 v[26:27], v[26:27], v[146:147] op_sel_hi:[1,0]
	v_pk_mul_f32 v[20:21], v[20:21], v[146:147] op_sel_hi:[1,0]
	v_pk_mul_f32 v[22:23], v[22:23], v[146:147] op_sel_hi:[1,0]
	v_pk_mul_f32 v[16:17], v[16:17], v[146:147] op_sel_hi:[1,0]
	v_pk_mul_f32 v[18:19], v[18:19], v[146:147] op_sel_hi:[1,0]
	v_max_f32_e32 v28, 0, v28
	v_max_f32_e32 v29, 0, v29
	v_max_f32_e32 v30, 0, v30
	v_max_f32_e32 v31, 0, v31
	v_max_f32_e32 v24, 0, v24
	v_max_f32_e32 v25, 0, v25
	v_max_f32_e32 v26, 0, v26
	v_max_f32_e32 v27, 0, v27
	v_max_f32_e32 v20, 0, v20
	v_max_f32_e32 v21, 0, v21
	v_max_f32_e32 v22, 0, v22
	v_max_f32_e32 v23, 0, v23
	v_max_f32_e32 v16, 0, v16
	v_max_f32_e32 v17, 0, v17
	v_max_f32_e32 v18, 0, v18
	v_max_f32_e32 v19, 0, v19
	v_pk_mul_f32 v[28:29], v[28:29], v[28:29]
	v_pk_mul_f32 v[30:31], v[30:31], v[30:31]
	v_pk_mul_f32 v[24:25], v[24:25], v[24:25]
	v_pk_mul_f32 v[26:27], v[26:27], v[26:27]
	v_pk_mul_f32 v[20:21], v[20:21], v[20:21]
	v_pk_mul_f32 v[22:23], v[22:23], v[22:23]
	v_pk_mul_f32 v[16:17], v[16:17], v[16:17]
	v_pk_mul_f32 v[18:19], v[18:19], v[18:19]
	v_cvt_pk_bf16_f32 v28, v28, v29
	v_cvt_pk_bf16_f32 v29, v30, v31
	v_cvt_pk_bf16_f32 v30, v24, v25
	v_cvt_pk_bf16_f32 v31, v26, v27
	global_store_dwordx4 v141, v[28:31], s[36:37]
	v_cvt_pk_bf16_f32 v20, v20, v21
	v_cvt_pk_bf16_f32 v21, v22, v23
	v_cvt_pk_bf16_f32 v22, v16, v17
	v_cvt_pk_bf16_f32 v23, v18, v19
	global_store_dwordx4 v141, v[20:23], s[36:37] offset:256
	v_fmamk_f32 v146, v191, 0x3a800000, v235
	v_rsq_f32_e32 v146, v146
	v_add_u32_e32 v141, 0x160000, v140
	v_pk_mul_f32 v[12:13], v[12:13], v[146:147] op_sel_hi:[1,0]
	v_pk_mul_f32 v[14:15], v[14:15], v[146:147] op_sel_hi:[1,0]
	v_pk_mul_f32 v[8:9], v[8:9], v[146:147] op_sel_hi:[1,0]
	v_pk_mul_f32 v[10:11], v[10:11], v[146:147] op_sel_hi:[1,0]
	v_pk_mul_f32 v[4:5], v[4:5], v[146:147] op_sel_hi:[1,0]
	v_pk_mul_f32 v[6:7], v[6:7], v[146:147] op_sel_hi:[1,0]
	v_pk_mul_f32 v[0:1], v[0:1], v[146:147] op_sel_hi:[1,0]
	v_pk_mul_f32 v[2:3], v[2:3], v[146:147] op_sel_hi:[1,0]
	v_max_f32_e32 v12, 0, v12
	v_max_f32_e32 v13, 0, v13
	v_max_f32_e32 v14, 0, v14
	v_max_f32_e32 v15, 0, v15
	v_max_f32_e32 v8, 0, v8
	v_max_f32_e32 v9, 0, v9
	v_max_f32_e32 v10, 0, v10
	v_max_f32_e32 v11, 0, v11
	v_max_f32_e32 v4, 0, v4
	v_max_f32_e32 v5, 0, v5
	v_max_f32_e32 v6, 0, v6
	v_max_f32_e32 v7, 0, v7
	v_max_f32_e32 v0, 0, v0
	v_max_f32_e32 v1, 0, v1
	v_max_f32_e32 v2, 0, v2
	v_max_f32_e32 v3, 0, v3
	v_pk_mul_f32 v[12:13], v[12:13], v[12:13]
	v_pk_mul_f32 v[14:15], v[14:15], v[14:15]
	v_pk_mul_f32 v[8:9], v[8:9], v[8:9]
	v_pk_mul_f32 v[10:11], v[10:11], v[10:11]
	v_pk_mul_f32 v[4:5], v[4:5], v[4:5]
	v_pk_mul_f32 v[6:7], v[6:7], v[6:7]
	v_pk_mul_f32 v[0:1], v[0:1], v[0:1]
	v_pk_mul_f32 v[2:3], v[2:3], v[2:3]
	v_cvt_pk_bf16_f32 v12, v12, v13
	v_cvt_pk_bf16_f32 v13, v14, v15
	v_cvt_pk_bf16_f32 v14, v8, v9
	v_cvt_pk_bf16_f32 v15, v10, v11
	global_store_dwordx4 v141, v[12:15], s[36:37]
	v_cvt_pk_bf16_f32 v4, v4, v5
	v_cvt_pk_bf16_f32 v5, v6, v7
	v_cvt_pk_bf16_f32 v6, v0, v1
	v_cvt_pk_bf16_f32 v7, v2, v3
	global_store_dwordx4 v141, v[4:7], s[36:37] offset:256
	s_andn2_b64 vcc, exec, s[38:39]
	s_cbranch_vccnz .LBB0_1136
	s_andn2_b64 vcc, exec, s[42:43]
	s_cbranch_vccnz .LBB0_1135
	s_barrier
	s_branch .LBB0_1135
